# C + all eight GEMM K-loop heads padded to byte phase 16 mod 64 (code placement)
# speedup vs baseline: 1.0032x; 1.0032x over previous
;     __device__ bool next(int i, Unit& u) const { if (i != 0) return false; return so.next(round, u); }
;     __device__ __forceinline__ bool next(int i, Unit& u) const { if (i > 0 || !on) return false; u.pm = pm; u.pn = 0; return true; }
; #define PG8_STAGE(bufoff, gbase, voff) do { _Pragma("unroll") for (int _i = 0; _i < 2; ++_i) \
;         __builtin_amdgcn_global_load_lds((const unsigned*)((const char*)(gbase) + (voff)[_i]), (PG8_LAS unsigned*)(lds + (bufoff) + ldsw + _i * 8192), 16, 0, 0); } while (0)
; #define PG8_LDA(dst, b, h) do { _Pragma("unroll") for (int m = 0; m < 4; ++m) _Pragma("unroll") for (int k = 0; k < 2; ++k) dst[m][k] = *(const PG8_LAS bf16x8*)(lds + PG8_SA(b, h) + aoff + m * 2048 + k * 1024); } while (0)
; #define PG8_LDB(dst, b, h) do { _Pragma("unroll") for (int n = 0; n < 2; ++n) _Pragma("unroll") for (int k = 0; k < 2; ++k) dst[n][k] = *(const PG8_LAS bf16x8*)(lds + PG8_SB(b, h) + boff + n * 2048 + k * 1024); } while (0)
; #define PG8_WAIT_V(n) asm volatile("s_waitcnt vmcnt(" #n ")" ::: "memory")
; #define PG8_WAIT_L(n) asm volatile("s_waitcnt lgkmcnt(" #n ")" ::: "memory")
; #define PG8_BAR __builtin_amdgcn_s_barrier()
; template <class Epi, class Sched, bool ALIGN_EPI = false, bool SP2 = false, bool MIDHOOK = false>
; __device__ __forceinline__ void gemm_phase(PG8_LAS unsigned char* lds, const Gemm g, const Sched& S, const Epi& E) {
;     ...
;         const bool has_next = S.next(ui + 1, nxt);
;         const char* nA = has_next ? (const char*)g.A + (size_t)nxt.pm * tstep : cA; const char* nB = has_next ? (const char*)g.Bt + (size_t)nxt.pn * tstep : cB;
;         for (int t = 0; t < nt; t += 2) {
;             if constexpr (MIDHOOK) { if (t == nt / 2) E.mid(acc, cur, wr, wc, fr, fq); }
;             const bool last = (t == nt - 2);
;             const char* a1 = cA + (size_t)(t + 1) * kstep;
;             const char* a2 = last ? nA : cA + (size_t)(t + 2) * kstep; const char* b2 = last ? nB : cB + (size_t)(t + 2) * kstep;
;             const char* a3 = a2 + kstep; const char* b3 = b2 + kstep;
;             if (last && has_next) S.a_ready(nxt);
;             if constexpr (SP2) {
;             PG8_LDB(B0, 0, 0); PG8_LDB(B1, 0, 1); PG8_SCHED; PG8_LDA(At, 0, 0); PG8_STAGE(PG8_SA(1, 1), a1 + hstep, voffA);
;             PG8_WAIT_V(8); PG8_WAIT_L(0); PG8_BAR; PG8_MMA(0, 0, At, B0); PG8_MMA(0, 1, At, B1); PG8_BAR; PG8_SCHED;
.LBB0_190:
	s_ashr_i32 s41, s40, 31
	s_lshl_b64 s[42:43], s[40:41], 19
	v_readlane_b32 s12, v243, 48
	v_readlane_b32 s13, v243, 49
	s_add_u32 s42, s12, s42
	s_addc_u32 s43, s13, s43
	s_and_b64 s[44:45], s[0:1], exec
	s_cselect_b32 s5, s43, s7
	s_cselect_b32 s41, s42, s6
	s_ashr_i32 s39, s38, 31
	s_lshl_b64 s[44:45], s[38:39], 19
	s_add_u32 s44, s24, s44
	s_addc_u32 s45, s25, s45
	s_and_b64 s[48:49], s[0:1], exec
	s_cselect_b32 s39, s45, s9
	s_cselect_b32 s62, s44, s8
	s_add_u32 s6, s6, 0x40080
	s_addc_u32 s7, s7, 0
	s_add_u32 s63, s8, 0x100
	v_mov_b32_e32 v0, 0
	s_addc_u32 s64, s9, 0
	s_mov_b32 s65, -2
	v_mov_b32_e32 v1, v0
	v_mov_b32_e32 v2, v0
	v_mov_b32_e32 v3, v0
	v_mov_b32_e32 v8, v0
	v_mov_b32_e32 v9, v0
	v_mov_b32_e32 v10, v0
	v_mov_b32_e32 v11, v0
	v_mov_b32_e32 v16, v0
	v_mov_b32_e32 v17, v0
	v_mov_b32_e32 v18, v0
	v_mov_b32_e32 v19, v0
	v_mov_b32_e32 v24, v0
	v_mov_b32_e32 v25, v0
	v_mov_b32_e32 v26, v0
	v_mov_b32_e32 v27, v0
	v_mov_b32_e32 v32, v0
	v_mov_b32_e32 v33, v0
	v_mov_b32_e32 v34, v0
	v_mov_b32_e32 v35, v0
	v_mov_b32_e32 v40, v0
	v_mov_b32_e32 v41, v0
	v_mov_b32_e32 v42, v0
	v_mov_b32_e32 v43, v0
	v_mov_b32_e32 v48, v0
	v_mov_b32_e32 v49, v0
	v_mov_b32_e32 v50, v0
	v_mov_b32_e32 v51, v0
	v_mov_b32_e32 v56, v0
	v_mov_b32_e32 v57, v0
	v_mov_b32_e32 v58, v0
	v_mov_b32_e32 v59, v0
	v_mov_b32_e32 v4, v0
	v_mov_b32_e32 v5, v0
	v_mov_b32_e32 v6, v0
	v_mov_b32_e32 v7, v0
	v_mov_b32_e32 v12, v0
	v_mov_b32_e32 v13, v0
	v_mov_b32_e32 v14, v0
	v_mov_b32_e32 v15, v0
	v_mov_b32_e32 v20, v0
	v_mov_b32_e32 v21, v0
	v_mov_b32_e32 v22, v0
	v_mov_b32_e32 v23, v0
	v_mov_b32_e32 v28, v0
	v_mov_b32_e32 v29, v0
	v_mov_b32_e32 v30, v0
	v_mov_b32_e32 v31, v0
	v_mov_b32_e32 v36, v0
	v_mov_b32_e32 v37, v0
	v_mov_b32_e32 v38, v0
	v_mov_b32_e32 v39, v0
	v_mov_b32_e32 v44, v0
	v_mov_b32_e32 v45, v0
	v_mov_b32_e32 v46, v0
	v_mov_b32_e32 v47, v0
	v_mov_b32_e32 v52, v0
	v_mov_b32_e32 v53, v0
	v_mov_b32_e32 v54, v0
	v_mov_b32_e32 v55, v0
	v_mov_b32_e32 v60, v0
	v_mov_b32_e32 v61, v0
	v_mov_b32_e32 v62, v0
	v_mov_b32_e32 v63, v0
	v_mov_b32_e32 v64, v0
	v_mov_b32_e32 v65, v0
	v_mov_b32_e32 v66, v0
	v_mov_b32_e32 v67, v0
	v_mov_b32_e32 v72, v0
	v_mov_b32_e32 v73, v0
	v_mov_b32_e32 v74, v0
	v_mov_b32_e32 v75, v0
	v_mov_b32_e32 v80, v0
	v_mov_b32_e32 v81, v0
	v_mov_b32_e32 v82, v0
	v_mov_b32_e32 v83, v0
	v_mov_b32_e32 v88, v0
	v_mov_b32_e32 v89, v0
	v_mov_b32_e32 v90, v0
	v_mov_b32_e32 v91, v0
	v_mov_b32_e32 v96, v0
	v_mov_b32_e32 v97, v0
	v_mov_b32_e32 v98, v0
	v_mov_b32_e32 v99, v0
	v_mov_b32_e32 v104, v0
	v_mov_b32_e32 v105, v0
	v_mov_b32_e32 v106, v0
	v_mov_b32_e32 v107, v0
	v_mov_b32_e32 v112, v0
	v_mov_b32_e32 v113, v0
	v_mov_b32_e32 v114, v0
	v_mov_b32_e32 v115, v0
	v_mov_b32_e32 v120, v0
	v_mov_b32_e32 v121, v0
	v_mov_b32_e32 v122, v0
	v_mov_b32_e32 v123, v0
	v_mov_b32_e32 v68, v0
	v_mov_b32_e32 v69, v0
	v_mov_b32_e32 v70, v0
	v_mov_b32_e32 v71, v0
	v_mov_b32_e32 v76, v0
	v_mov_b32_e32 v77, v0
	v_mov_b32_e32 v78, v0
	v_mov_b32_e32 v79, v0
	v_mov_b32_e32 v84, v0
	v_mov_b32_e32 v85, v0
	v_mov_b32_e32 v86, v0
	v_mov_b32_e32 v87, v0
	v_mov_b32_e32 v92, v0
	v_mov_b32_e32 v93, v0
	v_mov_b32_e32 v94, v0
	v_mov_b32_e32 v95, v0
	v_mov_b32_e32 v100, v0
	v_mov_b32_e32 v101, v0
	v_mov_b32_e32 v102, v0
	v_mov_b32_e32 v103, v0
	v_mov_b32_e32 v108, v0
	v_mov_b32_e32 v109, v0
	v_mov_b32_e32 v110, v0
	v_mov_b32_e32 v111, v0
	v_mov_b32_e32 v116, v0
	v_mov_b32_e32 v117, v0
	v_mov_b32_e32 v118, v0
	v_mov_b32_e32 v119, v0
	v_mov_b32_e32 v124, v0
	v_mov_b32_e32 v125, v0
	v_mov_b32_e32 v126, v0
	v_mov_b32_e32 v127, v0
	s_nop 0
	s_nop 0
	s_nop 0
	s_nop 0
	s_nop 0
	s_nop 0
	s_nop 0
	s_nop 0
	s_nop 0
	s_nop 0
.LBB0_191:
	ds_read_b128 v[128:131], v180
	s_waitcnt vmcnt(0)
	ds_read_b128 v[132:135], v180 offset:1024
	ds_read_b128 v[136:139], v180 offset:2048
	ds_read_b128 v[168:171], v180 offset:3072
	ds_read_b128 v[172:175], v181
	ds_read_b128 v[184:187], v181 offset:1024
	ds_read_b128 v[188:191], v181 offset:2048
	ds_read_b128 v[192:195], v181 offset:3072
	s_add_u32 s8, s6, 0xfffc0080
	s_addc_u32 s9, s7, -1
	s_cmp_eq_u32 s65, 12
	s_cselect_b32 s49, s5, s9
	s_cselect_b32 s48, s41, s8
	s_cselect_b32 s9, s39, s64
	s_cselect_b32 s8, s62, s63
	v_lshl_add_u64 v[230:231], s[6:7], 0, v[156:157]
	s_add_i32 m0, s47, 0xc000
	ds_read_b128 v[196:199], v182
	ds_read_b128 v[200:203], v182 offset:1024
	ds_read_b128 v[204:207], v182 offset:2048
	ds_read_b128 v[208:211], v182 offset:3072
	ds_read_b128 v[212:215], v182 offset:4096
	ds_read_b128 v[216:219], v182 offset:5120
	ds_read_b128 v[222:225], v182 offset:6144
	ds_read_b128 v[226:229], v182 offset:7168
	global_load_lds_dwordx4 v[230:231], off
	v_lshl_add_u64 v[230:231], s[6:7], 0, v[158:159]
	s_add_i32 m0, s47, 0xe000
	s_nop 0
	global_load_lds_dwordx4 v[230:231], off
	s_waitcnt vmcnt(8)
	s_waitcnt lgkmcnt(0)
	s_barrier
; #define PG8_STAGE(bufoff, gbase, voff) do { _Pragma("unroll") for (int _i = 0; _i < 2; ++_i) \
;         __builtin_amdgcn_global_load_lds((const unsigned*)((const char*)(gbase) + (voff)[_i]), (PG8_LAS unsigned*)(lds + (bufoff) + ldsw + _i * 8192), 16, 0, 0); } while (0)
; #define PG8_LDA(dst, b, h) do { _Pragma("unroll") for (int m = 0; m < 4; ++m) _Pragma("unroll") for (int k = 0; k < 2; ++k) dst[m][k] = *(const PG8_LAS bf16x8*)(lds + PG8_SA(b, h) + aoff + m * 2048 + k * 1024); } while (0)
; #define PG8_MMA(ai, bj, At, Bt) do { __builtin_amdgcn_s_setprio(1); _Pragma("unroll") for (int m = 0; m < 4; ++m) _Pragma("unroll") for (int n = 0; n < 2; ++n) _Pragma("unroll") for (int k = 0; k < 2; ++k) \
;         acc[ai][bj][m][n] = __builtin_amdgcn_mfma_f32_16x16x32_bf16(Bt[n][k], At[m][k], acc[ai][bj][m][n], 0, 0, 0); __builtin_amdgcn_s_setprio(0); } while (0)
; #define PG8_WAIT_V(n) asm volatile("s_waitcnt vmcnt(" #n ")" ::: "memory")
; #define PG8_WAIT_L(n) asm volatile("s_waitcnt lgkmcnt(" #n ")" ::: "memory")
; #define PG8_BAR __builtin_amdgcn_s_barrier()
; #define PG8_SCHED __builtin_amdgcn_sched_barrier(0)
; template <class Epi, class Sched, bool ALIGN_EPI = false, bool SP2 = false, bool MIDHOOK = false>
; __device__ __forceinline__ void gemm_phase(PG8_LAS unsigned char* lds, const Gemm g, const Sched& S, const Epi& E) {
;     ...
;             PG8_WAIT_V(8); PG8_WAIT_L(0); PG8_BAR; PG8_MMA(0, 0, At, B0); PG8_MMA(0, 1, At, B1); PG8_BAR; PG8_SCHED;
;             PG8_LDA(At, 0, 1); PG8_STAGE(PG8_SB(0, 0), b2, voffB); PG8_STAGE(PG8_SB(0, 1), b2 + hstep, voffB); PG8_STAGE(PG8_SA(0, 0), a2, voffA);
;             PG8_WAIT_V(8); PG8_WAIT_L(0); PG8_BAR; PG8_MMA(1, 0, At, B0); PG8_MMA(1, 1, At, B1); PG8_BAR; PG8_SCHED;
	s_setprio 1
	s_waitcnt lgkmcnt(0)
	v_mfma_f32_16x16x32_bf16 v[124:127], v[128:131], v[196:199], v[124:127]
	v_mfma_f32_16x16x32_bf16 v[116:119], v[136:139], v[196:199], v[116:119]
	v_mfma_f32_16x16x32_bf16 v[108:111], v[128:131], v[204:207], v[108:111]
	v_mfma_f32_16x16x32_bf16 v[100:103], v[136:139], v[204:207], v[100:103]
	v_mfma_f32_16x16x32_bf16 v[92:95], v[128:131], v[212:215], v[92:95]
	v_mfma_f32_16x16x32_bf16 v[84:87], v[136:139], v[212:215], v[84:87]
	v_mfma_f32_16x16x32_bf16 v[76:79], v[128:131], v[222:225], v[76:79]
	v_mfma_f32_16x16x32_bf16 v[68:71], v[136:139], v[222:225], v[68:71]
	v_mfma_f32_16x16x32_bf16 v[124:127], v[132:135], v[200:203], v[124:127]
	v_mfma_f32_16x16x32_bf16 v[116:119], v[168:171], v[200:203], v[116:119]
	v_mfma_f32_16x16x32_bf16 v[108:111], v[132:135], v[208:211], v[108:111]
	v_mfma_f32_16x16x32_bf16 v[100:103], v[168:171], v[208:211], v[100:103]
	v_mfma_f32_16x16x32_bf16 v[92:95], v[132:135], v[216:219], v[92:95]
	v_mfma_f32_16x16x32_bf16 v[84:87], v[168:171], v[216:219], v[84:87]
	v_mfma_f32_16x16x32_bf16 v[76:79], v[132:135], v[226:229], v[76:79]
	v_mfma_f32_16x16x32_bf16 v[68:71], v[168:171], v[226:229], v[68:71]
	s_setprio 0
	s_setprio 1
	v_mfma_f32_16x16x32_bf16 v[120:123], v[172:175], v[196:199], v[120:123]
	v_mfma_f32_16x16x32_bf16 v[112:115], v[188:191], v[196:199], v[112:115]
	v_mfma_f32_16x16x32_bf16 v[104:107], v[172:175], v[204:207], v[104:107]
	v_mfma_f32_16x16x32_bf16 v[96:99], v[188:191], v[204:207], v[96:99]
	v_mfma_f32_16x16x32_bf16 v[88:91], v[172:175], v[212:215], v[88:91]
	v_mfma_f32_16x16x32_bf16 v[80:83], v[188:191], v[212:215], v[80:83]
	v_mfma_f32_16x16x32_bf16 v[72:75], v[172:175], v[222:225], v[72:75]
	v_mfma_f32_16x16x32_bf16 v[64:67], v[188:191], v[222:225], v[64:67]
	v_mfma_f32_16x16x32_bf16 v[120:123], v[184:187], v[200:203], v[120:123]
	v_mfma_f32_16x16x32_bf16 v[112:115], v[192:195], v[200:203], v[112:115]
	v_mfma_f32_16x16x32_bf16 v[104:107], v[184:187], v[208:211], v[104:107]
	v_mfma_f32_16x16x32_bf16 v[96:99], v[192:195], v[208:211], v[96:99]
	v_mfma_f32_16x16x32_bf16 v[88:91], v[184:187], v[216:219], v[88:91]
	v_mfma_f32_16x16x32_bf16 v[80:83], v[192:195], v[216:219], v[80:83]
	v_mfma_f32_16x16x32_bf16 v[72:75], v[184:187], v[226:229], v[72:75]
	v_mfma_f32_16x16x32_bf16 v[64:67], v[192:195], v[226:229], v[64:67]
	s_setprio 0
	s_barrier
	s_add_i32 s66, s58, s3
	v_lshl_add_u64 v[230:231], s[8:9], 0, v[142:143]
	s_mov_b32 m0, s66
	ds_read_b128 v[196:199], v182 offset:16384
	ds_read_b128 v[200:203], v182 offset:17408
	ds_read_b128 v[204:207], v182 offset:18432
	ds_read_b128 v[208:211], v182 offset:19456
	ds_read_b128 v[212:215], v182 offset:20480
	ds_read_b128 v[216:219], v182 offset:21504
	ds_read_b128 v[222:225], v182 offset:22528
	ds_read_b128 v[226:229], v182 offset:23552
	global_load_lds_dwordx4 v[230:231], off
	s_add_i32 m0, s66, 0x2000
	s_add_u32 s66, s8, 0x40000
	v_lshl_add_u64 v[232:233], s[8:9], 0, v[146:147]
	s_addc_u32 s67, s9, 0
	s_add_i32 s68, s59, s3
	global_load_lds_dwordx4 v[232:233], off
	v_lshl_add_u64 v[234:235], s[66:67], 0, v[142:143]
	s_mov_b32 m0, s68
	v_lshl_add_u64 v[236:237], s[48:49], 0, v[144:145]
	global_load_lds_dwordx4 v[234:235], off
	v_lshl_add_u64 v[234:235], s[66:67], 0, v[146:147]
	s_add_i32 m0, s68, 0x2000
	s_nop 0
	global_load_lds_dwordx4 v[234:235], off
	v_lshl_add_u64 v[234:235], s[48:49], 0, v[140:141]
	s_mov_b32 m0, s47
	s_nop 0
	global_load_lds_dwordx4 v[234:235], off
	s_mov_b32 m0, s50
	s_nop 0
	global_load_lds_dwordx4 v[236:237], off
	s_waitcnt vmcnt(8)
	s_waitcnt lgkmcnt(0)
	s_barrier
	s_setprio 1
	s_waitcnt lgkmcnt(0)
	v_mfma_f32_16x16x32_bf16 v[60:63], v[128:131], v[196:199], v[60:63]
	v_mfma_f32_16x16x32_bf16 v[52:55], v[136:139], v[196:199], v[52:55]
	v_mfma_f32_16x16x32_bf16 v[44:47], v[128:131], v[204:207], v[44:47]
	v_mfma_f32_16x16x32_bf16 v[36:39], v[136:139], v[204:207], v[36:39]
	v_mfma_f32_16x16x32_bf16 v[28:31], v[128:131], v[212:215], v[28:31]
	v_mfma_f32_16x16x32_bf16 v[20:23], v[136:139], v[212:215], v[20:23]
	v_mfma_f32_16x16x32_bf16 v[12:15], v[128:131], v[222:225], v[12:15]
	v_mfma_f32_16x16x32_bf16 v[4:7], v[136:139], v[222:225], v[4:7]
	v_mfma_f32_16x16x32_bf16 v[60:63], v[132:135], v[200:203], v[60:63]
	v_mfma_f32_16x16x32_bf16 v[52:55], v[168:171], v[200:203], v[52:55]
	v_mfma_f32_16x16x32_bf16 v[44:47], v[132:135], v[208:211], v[44:47]
	v_mfma_f32_16x16x32_bf16 v[36:39], v[168:171], v[208:211], v[36:39]
	v_mfma_f32_16x16x32_bf16 v[28:31], v[132:135], v[216:219], v[28:31]
	v_mfma_f32_16x16x32_bf16 v[20:23], v[168:171], v[216:219], v[20:23]
	v_mfma_f32_16x16x32_bf16 v[12:15], v[132:135], v[226:229], v[12:15]
	v_mfma_f32_16x16x32_bf16 v[4:7], v[168:171], v[226:229], v[4:7]
	s_setprio 0
	s_setprio 1
	v_mfma_f32_16x16x32_bf16 v[56:59], v[172:175], v[196:199], v[56:59]
	v_mfma_f32_16x16x32_bf16 v[48:51], v[188:191], v[196:199], v[48:51]
	v_mfma_f32_16x16x32_bf16 v[40:43], v[172:175], v[204:207], v[40:43]
	v_mfma_f32_16x16x32_bf16 v[32:35], v[188:191], v[204:207], v[32:35]
	v_mfma_f32_16x16x32_bf16 v[24:27], v[172:175], v[212:215], v[24:27]
	v_mfma_f32_16x16x32_bf16 v[16:19], v[188:191], v[212:215], v[16:19]
	v_mfma_f32_16x16x32_bf16 v[8:11], v[172:175], v[222:225], v[8:11]
	v_mfma_f32_16x16x32_bf16 v[0:3], v[188:191], v[222:225], v[0:3]
	v_mfma_f32_16x16x32_bf16 v[56:59], v[184:187], v[200:203], v[56:59]
	v_mfma_f32_16x16x32_bf16 v[48:51], v[192:195], v[200:203], v[48:51]
	v_mfma_f32_16x16x32_bf16 v[40:43], v[184:187], v[208:211], v[40:43]
	v_mfma_f32_16x16x32_bf16 v[32:35], v[192:195], v[208:211], v[32:35]
	v_mfma_f32_16x16x32_bf16 v[24:27], v[184:187], v[216:219], v[24:27]
	v_mfma_f32_16x16x32_bf16 v[16:19], v[192:195], v[216:219], v[16:19]
	v_mfma_f32_16x16x32_bf16 v[8:11], v[184:187], v[226:229], v[8:11]
	v_mfma_f32_16x16x32_bf16 v[0:3], v[192:195], v[226:229], v[0:3]
	s_setprio 0
	s_barrier
; #define PG8_STAGE(bufoff, gbase, voff) do { _Pragma("unroll") for (int _i = 0; _i < 2; ++_i) \
;         __builtin_amdgcn_global_load_lds((const unsigned*)((const char*)(gbase) + (voff)[_i]), (PG8_LAS unsigned*)(lds + (bufoff) + ldsw + _i * 8192), 16, 0, 0); } while (0)
; #define PG8_LDA(dst, b, h) do { _Pragma("unroll") for (int m = 0; m < 4; ++m) _Pragma("unroll") for (int k = 0; k < 2; ++k) dst[m][k] = *(const PG8_LAS bf16x8*)(lds + PG8_SA(b, h) + aoff + m * 2048 + k * 1024); } while (0)
; #define PG8_LDB(dst, b, h) do { _Pragma("unroll") for (int n = 0; n < 2; ++n) _Pragma("unroll") for (int k = 0; k < 2; ++k) dst[n][k] = *(const PG8_LAS bf16x8*)(lds + PG8_SB(b, h) + boff + n * 2048 + k * 1024); } while (0)
; #define PG8_MMA(ai, bj, At, Bt) do { __builtin_amdgcn_s_setprio(1); _Pragma("unroll") for (int m = 0; m < 4; ++m) _Pragma("unroll") for (int n = 0; n < 2; ++n) _Pragma("unroll") for (int k = 0; k < 2; ++k) \
;         acc[ai][bj][m][n] = __builtin_amdgcn_mfma_f32_16x16x32_bf16(Bt[n][k], At[m][k], acc[ai][bj][m][n], 0, 0, 0); __builtin_amdgcn_s_setprio(0); } while (0)
; #define PG8_WAIT_V(n) asm volatile("s_waitcnt vmcnt(" #n ")" ::: "memory")
; #define PG8_WAIT_L(n) asm volatile("s_waitcnt lgkmcnt(" #n ")" ::: "memory")
; #define PG8_BAR __builtin_amdgcn_s_barrier()
; #define PG8_SCHED __builtin_amdgcn_sched_barrier(0)
; template <class Epi, class Sched, bool ALIGN_EPI = false, bool SP2 = false, bool MIDHOOK = false>
; __device__ __forceinline__ void gemm_phase(PG8_LAS unsigned char* lds, const Gemm g, const Sched& S, const Epi& E) {
;     ...
;             PG8_LDB(B0, 1, 0); PG8_LDB(B1, 1, 1); PG8_SCHED; PG8_LDA(At, 1, 0); PG8_STAGE(PG8_SA(0, 1), a2 + hstep, voffA);
;             PG8_WAIT_V(8); PG8_WAIT_L(0); PG8_BAR; PG8_MMA(0, 0, At, B0); PG8_MMA(0, 1, At, B1); PG8_BAR; PG8_SCHED;
	s_add_i32 s66, 0, 0x18000
	v_add_u32_e32 v148, s66, v177
	s_add_i32 s67, 0, 0x1c000
	ds_read_b128 v[128:131], v148
	ds_read_b128 v[132:135], v148 offset:1024
	ds_read_b128 v[136:139], v148 offset:2048
	ds_read_b128 v[168:171], v148 offset:3072
	v_add_u32_e32 v148, s67, v177
	ds_read_b128 v[172:175], v148
	ds_read_b128 v[184:187], v148 offset:1024
	ds_read_b128 v[188:191], v148 offset:2048
	ds_read_b128 v[192:195], v148 offset:3072
	s_add_u32 s48, s48, 0x40000
	s_addc_u32 s49, s49, 0
	s_mov_b32 m0, s51
	v_lshl_add_u64 v[238:239], s[48:49], 0, v[140:141]
	ds_read_b128 v[196:199], v182 offset:32768
	ds_read_b128 v[200:203], v182 offset:33792
	ds_read_b128 v[204:207], v182 offset:34816
	ds_read_b128 v[208:211], v182 offset:35840
	ds_read_b128 v[212:215], v182 offset:36864
	ds_read_b128 v[216:219], v182 offset:37888
	ds_read_b128 v[222:225], v182 offset:38912
	ds_read_b128 v[226:229], v182 offset:39936
	global_load_lds_dwordx4 v[238:239], off
	v_lshl_add_u64 v[238:239], s[48:49], 0, v[144:145]
	s_mov_b32 m0, s52
	s_nop 0
	global_load_lds_dwordx4 v[238:239], off
	s_waitcnt vmcnt(8)
	s_waitcnt lgkmcnt(0)
	s_barrier
	s_setprio 1
	s_waitcnt lgkmcnt(0)
	v_mfma_f32_16x16x32_bf16 v[124:127], v[128:131], v[196:199], v[124:127]
	v_mfma_f32_16x16x32_bf16 v[116:119], v[136:139], v[196:199], v[116:119]
	v_mfma_f32_16x16x32_bf16 v[108:111], v[128:131], v[204:207], v[108:111]
	v_mfma_f32_16x16x32_bf16 v[100:103], v[136:139], v[204:207], v[100:103]
	v_mfma_f32_16x16x32_bf16 v[92:95], v[128:131], v[212:215], v[92:95]
	v_mfma_f32_16x16x32_bf16 v[84:87], v[136:139], v[212:215], v[84:87]
	v_mfma_f32_16x16x32_bf16 v[76:79], v[128:131], v[222:225], v[76:79]
	v_mfma_f32_16x16x32_bf16 v[68:71], v[136:139], v[222:225], v[68:71]
	v_mfma_f32_16x16x32_bf16 v[124:127], v[132:135], v[200:203], v[124:127]
	v_mfma_f32_16x16x32_bf16 v[116:119], v[168:171], v[200:203], v[116:119]
	v_mfma_f32_16x16x32_bf16 v[108:111], v[132:135], v[208:211], v[108:111]
	v_mfma_f32_16x16x32_bf16 v[100:103], v[168:171], v[208:211], v[100:103]
	v_mfma_f32_16x16x32_bf16 v[92:95], v[132:135], v[216:219], v[92:95]
	v_mfma_f32_16x16x32_bf16 v[84:87], v[168:171], v[216:219], v[84:87]
	v_mfma_f32_16x16x32_bf16 v[76:79], v[132:135], v[226:229], v[76:79]
	v_mfma_f32_16x16x32_bf16 v[68:71], v[168:171], v[226:229], v[68:71]
	s_setprio 0
	s_setprio 1
	v_mfma_f32_16x16x32_bf16 v[120:123], v[172:175], v[196:199], v[120:123]
	v_mfma_f32_16x16x32_bf16 v[112:115], v[188:191], v[196:199], v[112:115]
	v_mfma_f32_16x16x32_bf16 v[104:107], v[172:175], v[204:207], v[104:107]
	v_mfma_f32_16x16x32_bf16 v[96:99], v[188:191], v[204:207], v[96:99]
	v_mfma_f32_16x16x32_bf16 v[88:91], v[172:175], v[212:215], v[88:91]
	v_mfma_f32_16x16x32_bf16 v[80:83], v[188:191], v[212:215], v[80:83]
	v_mfma_f32_16x16x32_bf16 v[72:75], v[172:175], v[222:225], v[72:75]
	v_mfma_f32_16x16x32_bf16 v[64:67], v[188:191], v[222:225], v[64:67]
	v_mfma_f32_16x16x32_bf16 v[120:123], v[184:187], v[200:203], v[120:123]
	v_mfma_f32_16x16x32_bf16 v[112:115], v[192:195], v[200:203], v[112:115]
	v_mfma_f32_16x16x32_bf16 v[104:107], v[184:187], v[208:211], v[104:107]
	v_mfma_f32_16x16x32_bf16 v[96:99], v[192:195], v[208:211], v[96:99]
	v_mfma_f32_16x16x32_bf16 v[88:91], v[184:187], v[216:219], v[88:91]
	v_mfma_f32_16x16x32_bf16 v[80:83], v[192:195], v[216:219], v[80:83]
	v_mfma_f32_16x16x32_bf16 v[72:75], v[184:187], v[226:229], v[72:75]
	v_mfma_f32_16x16x32_bf16 v[64:67], v[192:195], v[226:229], v[64:67]
	s_setprio 0
	s_barrier
; #define PG8_STAGE(bufoff, gbase, voff) do { _Pragma("unroll") for (int _i = 0; _i < 2; ++_i) \
;         __builtin_amdgcn_global_load_lds((const unsigned*)((const char*)(gbase) + (voff)[_i]), (PG8_LAS unsigned*)(lds + (bufoff) + ldsw + _i * 8192), 16, 0, 0); } while (0)
; #define PG8_LDA(dst, b, h) do { _Pragma("unroll") for (int m = 0; m < 4; ++m) _Pragma("unroll") for (int k = 0; k < 2; ++k) dst[m][k] = *(const PG8_LAS bf16x8*)(lds + PG8_SA(b, h) + aoff + m * 2048 + k * 1024); } while (0)
; #define PG8_MMA(ai, bj, At, Bt) do { __builtin_amdgcn_s_setprio(1); _Pragma("unroll") for (int m = 0; m < 4; ++m) _Pragma("unroll") for (int n = 0; n < 2; ++n) _Pragma("unroll") for (int k = 0; k < 2; ++k) \
;         acc[ai][bj][m][n] = __builtin_amdgcn_mfma_f32_16x16x32_bf16(Bt[n][k], At[m][k], acc[ai][bj][m][n], 0, 0, 0); __builtin_amdgcn_s_setprio(0); } while (0)
; #define PG8_WAIT_V(n) asm volatile("s_waitcnt vmcnt(" #n ")" ::: "memory")
; #define PG8_WAIT_L(n) asm volatile("s_waitcnt lgkmcnt(" #n ")" ::: "memory")
; #define PG8_BAR __builtin_amdgcn_s_barrier()
; #define PG8_SCHED __builtin_amdgcn_sched_barrier(0)
; template <class Epi, class Sched, bool ALIGN_EPI = false, bool SP2 = false, bool MIDHOOK = false>
; __device__ __forceinline__ void gemm_phase(PG8_LAS unsigned char* lds, const Gemm g, const Sched& S, const Epi& E) {
;     ...
;             PG8_LDA(At, 1, 1); PG8_STAGE(PG8_SB(1, 0), b3, voffB); PG8_STAGE(PG8_SB(1, 1), b3 + hstep, voffB); PG8_STAGE(PG8_SA(1, 0), a3, voffA);
;             PG8_WAIT_V(8); PG8_WAIT_L(0); PG8_BAR; PG8_MMA(1, 0, At, B0); PG8_MMA(1, 1, At, B1); PG8_BAR; PG8_SCHED;
;     ...
;         if constexpr (ALIGN_EPI) { if (wr == 0) PG8_BAR; }
	s_add_i32 s48, s66, s3
	v_lshl_add_u64 v[230:231], v[230:231], 0, s[34:35]
	s_mov_b32 m0, s48
	ds_read_b128 v[196:199], v182 offset:49152
	ds_read_b128 v[200:203], v182 offset:50176
	ds_read_b128 v[204:207], v182 offset:51200
	ds_read_b128 v[208:211], v182 offset:52224
	ds_read_b128 v[212:215], v182 offset:53248
	ds_read_b128 v[216:219], v182 offset:54272
	ds_read_b128 v[222:225], v182 offset:55296
	ds_read_b128 v[226:229], v182 offset:56320
	global_load_lds_dwordx4 v[230:231], off
	s_add_i32 m0, s48, 0x2000
	s_add_u32 s8, s8, 0x40080
	v_lshl_add_u64 v[230:231], v[232:233], 0, s[34:35]
	s_addc_u32 s9, s9, 0
	s_add_i32 s48, s67, s3
	global_load_lds_dwordx4 v[230:231], off
	v_lshl_add_u64 v[230:231], s[8:9], 0, v[142:143]
	s_mov_b32 m0, s48
	s_nop 0
	global_load_lds_dwordx4 v[230:231], off
	v_lshl_add_u64 v[230:231], s[8:9], 0, v[146:147]
	s_add_i32 m0, s48, 0x2000
	s_nop 0
	global_load_lds_dwordx4 v[230:231], off
	v_lshl_add_u64 v[230:231], v[234:235], 0, s[34:35]
	s_mov_b32 m0, s54
	s_nop 0
	global_load_lds_dwordx4 v[230:231], off
	v_lshl_add_u64 v[230:231], v[236:237], 0, s[34:35]
	s_mov_b32 m0, s55
	s_nop 0
	global_load_lds_dwordx4 v[230:231], off
	s_waitcnt vmcnt(8)
	s_waitcnt lgkmcnt(0)
	s_barrier
	s_setprio 1
	s_waitcnt lgkmcnt(0)
	v_mfma_f32_16x16x32_bf16 v[60:63], v[128:131], v[196:199], v[60:63]
	v_mfma_f32_16x16x32_bf16 v[52:55], v[136:139], v[196:199], v[52:55]
	v_mfma_f32_16x16x32_bf16 v[44:47], v[128:131], v[204:207], v[44:47]
	v_mfma_f32_16x16x32_bf16 v[36:39], v[136:139], v[204:207], v[36:39]
	v_mfma_f32_16x16x32_bf16 v[28:31], v[128:131], v[212:215], v[28:31]
	v_mfma_f32_16x16x32_bf16 v[20:23], v[136:139], v[212:215], v[20:23]
	v_mfma_f32_16x16x32_bf16 v[12:15], v[128:131], v[222:225], v[12:15]
	v_mfma_f32_16x16x32_bf16 v[4:7], v[136:139], v[222:225], v[4:7]
	v_mfma_f32_16x16x32_bf16 v[60:63], v[132:135], v[200:203], v[60:63]
	v_mfma_f32_16x16x32_bf16 v[52:55], v[168:171], v[200:203], v[52:55]
	v_mfma_f32_16x16x32_bf16 v[44:47], v[132:135], v[208:211], v[44:47]
	v_mfma_f32_16x16x32_bf16 v[36:39], v[168:171], v[208:211], v[36:39]
	v_mfma_f32_16x16x32_bf16 v[28:31], v[132:135], v[216:219], v[28:31]
	v_mfma_f32_16x16x32_bf16 v[20:23], v[168:171], v[216:219], v[20:23]
	v_mfma_f32_16x16x32_bf16 v[12:15], v[132:135], v[226:229], v[12:15]
	v_mfma_f32_16x16x32_bf16 v[4:7], v[168:171], v[226:229], v[4:7]
	s_setprio 0
	s_setprio 1
	v_mfma_f32_16x16x32_bf16 v[56:59], v[172:175], v[196:199], v[56:59]
	v_mfma_f32_16x16x32_bf16 v[48:51], v[188:191], v[196:199], v[48:51]
	v_mfma_f32_16x16x32_bf16 v[40:43], v[172:175], v[204:207], v[40:43]
	v_mfma_f32_16x16x32_bf16 v[32:35], v[188:191], v[204:207], v[32:35]
	v_mfma_f32_16x16x32_bf16 v[24:27], v[172:175], v[212:215], v[24:27]
	v_mfma_f32_16x16x32_bf16 v[16:19], v[188:191], v[212:215], v[16:19]
	v_mfma_f32_16x16x32_bf16 v[8:11], v[172:175], v[222:225], v[8:11]
	v_mfma_f32_16x16x32_bf16 v[0:3], v[188:191], v[222:225], v[0:3]
	v_mfma_f32_16x16x32_bf16 v[56:59], v[184:187], v[200:203], v[56:59]
	v_mfma_f32_16x16x32_bf16 v[48:51], v[192:195], v[200:203], v[48:51]
	v_mfma_f32_16x16x32_bf16 v[40:43], v[184:187], v[208:211], v[40:43]
	v_mfma_f32_16x16x32_bf16 v[32:35], v[192:195], v[208:211], v[32:35]
	v_mfma_f32_16x16x32_bf16 v[24:27], v[184:187], v[216:219], v[24:27]
	v_mfma_f32_16x16x32_bf16 v[16:19], v[192:195], v[216:219], v[16:19]
	v_mfma_f32_16x16x32_bf16 v[8:11], v[184:187], v[226:229], v[8:11]
	v_mfma_f32_16x16x32_bf16 v[0:3], v[192:195], v[226:229], v[0:3]
	s_setprio 0
	s_barrier
	s_add_i32 s65, s65, 2
	s_add_u32 s6, s6, 0x100
	s_addc_u32 s7, s7, 0
	s_add_u32 s63, s63, 0x100
	s_addc_u32 s64, s64, 0
	s_cmp_gt_u32 s65, 13
	s_cbranch_scc0 .LBB0_191
	s_and_b64 vcc, exec, s[36:37]
	s_cbranch_vccz .LBB0_194
	s_barrier
